# P10 attention QK^T: LDS fragment reads hoisted into spare VGPRs, counted lgkmcnt instead of read-wait-MFMA ladder (4 sections)
# baseline (speedup 1.0000x reference)
; template <int KB>
; __device__ __forceinline__ void qkt(f32x16& p0, f32x16& p1, const char* K_lds, int r32, int hi, const bf16x8* qs) {
;     p0 = f32x16{}; p1 = f32x16{};
;     const char* kb[4];
; #pragma unroll
;     for (int dd = 0; dd < 4; ++dd) kb[dd] = K_lds + KB * SHM_K + KSWZ(r32, (dd * 16 + hi * 8) * 2);
; #pragma unroll
;     for (int d0 = 0; d0 < 8; ++d0) { const char* a = kb[d0 & 3] + (d0 >> 2) * 128;
;         bf16x8 b0 = *reinterpret_cast<const bf16x8*>(a);
;         bf16x8 b1 = *reinterpret_cast<const bf16x8*>(a + 32 * 256);
;         const bf16x8 qf = qs[d0 * 64];
;         p0 = __builtin_amdgcn_mfma_f32_32x32x16_bf16(b0, qf, p0, 0, 0, 0);
;         p1 = __builtin_amdgcn_mfma_f32_32x32x16_bf16(b1, qf, p1, 0, 0, 0); }
; template <int BUF>
; __device__ __forceinline__ void fox_tile(f32x16* o, float& m_reg, float& l_reg, const char* lds, const float* ckl, float* al_l, int vb0, const bf16x8* qr, float cq, int qpos, int kb0, bool need_mask, int r32, int hi) {
;     ...
;     const float* ck = ckl + kb0 + 4 * hi;
; #pragma unroll
;     for (int g = 0; g < 4; ++g) { const f32x4 c0 = *(const f32x4*)(ck + 8 * g), c1 = *(const f32x4*)(ck + 32 + 8 * g);
; #pragma unroll
;         for (int e = 0; e < 4; ++e) { p0[4 * g + e] += cq - c0[e]; p1[4 * g + e] += cq - c1[e]; } }
.LBB0_1335:
	s_add_i32 s0, s72, 63
	s_cmp_le_i32 s0, s40
	s_waitcnt vmcnt(0)
	ds_read_b128 v[232:235], v162 offset:288
	ds_read_b128 v[240:243], v162 offset:320
	ds_read_b128 v[244:247], v162 offset:352
	ds_read_b128 v[248:251], v162 offset:256
	ds_read_b128 v[96:99], v152
	ds_read_b128 v[212:215], v163 offset:32768
	ds_read_b128 v[104:107], v152 offset:1024
	ds_read_b128 v[216:219], v164 offset:32768
	ds_read_b128 v[108:111], v152 offset:2048
	ds_read_b128 v[220:223], v165 offset:32768
	ds_read_b128 v[178:181], v152 offset:3072
	ds_read_b128 v[224:227], v166 offset:32768
	ds_read_b128 v[182:185], v152 offset:4096
	ds_read_b128 v[228:231], v163 offset:32896
	s_waitcnt lgkmcnt(10)
	v_sub_f32_e32 v133, v69, v233
	v_sub_f32_e32 v132, v68, v232
	v_sub_f32_e32 v131, v71, v235
	v_sub_f32_e32 v130, v70, v234
	v_sub_f32_e32 v127, v73, v241
	v_sub_f32_e32 v126, v72, v240
	v_sub_f32_e32 v125, v75, v243
	v_sub_f32_e32 v124, v74, v242
	v_sub_f32_e32 v123, v77, v245
	v_sub_f32_e32 v122, v76, v244
	v_sub_f32_e32 v121, v79, v247
	v_sub_f32_e32 v120, v78, v246
	v_sub_f32_e32 v135, v67, v251
	v_sub_f32_e32 v134, v66, v250
	v_sub_f32_e32 v137, v65, v249
	v_sub_f32_e32 v136, v64, v248
	s_waitcnt lgkmcnt(8)
	v_mfma_f32_32x32x16_bf16 v[80:95], v[212:215], v[96:99], 0
	ds_read_b128 v[186:189], v152 offset:5120
	ds_read_b128 v[232:235], v164 offset:32896
	s_waitcnt lgkmcnt(8)
	v_mfma_f32_32x32x16_bf16 v[80:95], v[216:219], v[104:107], v[80:95]
	ds_read_b128 v[190:193], v152 offset:6144
	ds_read_b128 v[240:243], v165 offset:32896
	s_waitcnt lgkmcnt(8)
	v_mfma_f32_32x32x16_bf16 v[80:95], v[220:223], v[108:111], v[80:95]
	ds_read_b128 v[194:197], v152 offset:7168
	ds_read_b128 v[244:247], v166 offset:32896
	s_waitcnt lgkmcnt(8)
	v_mfma_f32_32x32x16_bf16 v[80:95], v[224:227], v[178:181], v[80:95]
	s_waitcnt lgkmcnt(6)
	v_mfma_f32_32x32x16_bf16 v[80:95], v[228:231], v[182:185], v[80:95]
	s_waitcnt lgkmcnt(4)
	v_mfma_f32_32x32x16_bf16 v[80:95], v[232:235], v[186:189], v[80:95]
	s_waitcnt lgkmcnt(2)
	v_mfma_f32_32x32x16_bf16 v[80:95], v[240:243], v[190:193], v[80:95]
	s_waitcnt lgkmcnt(0)
	v_mfma_f32_32x32x16_bf16 v[80:95], v[244:247], v[194:197], v[80:95]
	ds_read_b128 v[212:215], v163 offset:40960
	ds_read_b128 v[216:219], v164 offset:40960
	ds_read_b128 v[220:223], v165 offset:40960
	ds_read_b128 v[224:227], v166 offset:40960
	ds_read_b128 v[228:231], v163 offset:41088
	ds_read_b128 v[232:235], v164 offset:41088
	ds_read_b128 v[240:243], v165 offset:41088
	ds_read_b128 v[244:247], v166 offset:41088
	s_nop 11
	v_pk_add_f32 v[136:137], v[80:81], v[136:137]
	v_pk_add_f32 v[134:135], v[82:83], v[134:135]
	v_pk_add_f32 v[120:121], v[94:95], v[120:121]
	v_pk_add_f32 v[122:123], v[92:93], v[122:123]
	v_pk_add_f32 v[124:125], v[90:91], v[124:125]
	v_pk_add_f32 v[126:127], v[88:89], v[126:127]
	v_pk_add_f32 v[130:131], v[86:87], v[130:131]
	v_pk_add_f32 v[132:133], v[84:85], v[132:133]
	s_waitcnt lgkmcnt(7)
	v_mfma_f32_32x32x16_bf16 v[80:95], v[212:215], v[96:99], 0
	s_waitcnt lgkmcnt(6)
	v_mfma_f32_32x32x16_bf16 v[80:95], v[216:219], v[104:107], v[80:95]
	s_waitcnt lgkmcnt(5)
	v_mfma_f32_32x32x16_bf16 v[80:95], v[220:223], v[108:111], v[80:95]
	s_waitcnt lgkmcnt(4)
	v_mfma_f32_32x32x16_bf16 v[80:95], v[224:227], v[178:181], v[80:95]
	ds_read_b128 v[212:215], v162 offset:416
	ds_read_b128 v[216:219], v162 offset:448
	ds_read_b128 v[220:223], v162 offset:480
	ds_read_b128 v[224:227], v162 offset:384
	s_waitcnt lgkmcnt(7)
	v_mfma_f32_32x32x16_bf16 v[80:95], v[228:231], v[182:185], v[80:95]
	s_waitcnt lgkmcnt(6)
	v_mfma_f32_32x32x16_bf16 v[80:95], v[232:235], v[186:189], v[80:95]
	s_waitcnt lgkmcnt(5)
	v_mfma_f32_32x32x16_bf16 v[80:95], v[240:243], v[190:193], v[80:95]
	s_waitcnt lgkmcnt(4)
	v_mfma_f32_32x32x16_bf16 v[80:95], v[244:247], v[194:197], v[80:95]
	s_nop 3
	s_waitcnt lgkmcnt(3)
	v_sub_f32_e32 v101, v69, v213
	v_sub_f32_e32 v100, v68, v212
	v_sub_f32_e32 v103, v71, v215
	v_sub_f32_e32 v102, v70, v214
	s_nop 4
	v_pk_add_f32 v[84:85], v[84:85], v[100:101]
	v_pk_add_f32 v[86:87], v[86:87], v[102:103]
	s_waitcnt lgkmcnt(2)
	v_sub_f32_e32 v105, v73, v217
	v_sub_f32_e32 v104, v72, v216
	v_sub_f32_e32 v107, v75, v219
	v_sub_f32_e32 v106, v74, v218
	v_pk_add_f32 v[90:91], v[90:91], v[106:107]
	v_pk_add_f32 v[88:89], v[88:89], v[104:105]
	s_waitcnt lgkmcnt(1)
	v_sub_f32_e32 v109, v77, v221
	v_sub_f32_e32 v108, v76, v220
	v_sub_f32_e32 v111, v79, v223
	v_sub_f32_e32 v110, v78, v222
	v_pk_add_f32 v[92:93], v[92:93], v[108:109]
	s_waitcnt lgkmcnt(0)
	v_sub_f32_e32 v97, v65, v225
	v_sub_f32_e32 v96, v64, v224
	v_pk_add_f32 v[138:139], v[80:81], v[96:97]
	v_pk_add_f32 v[80:81], v[94:95], v[110:111]
	v_lshl_add_u64 v[94:95], v[118:119], 0, v[112:113]
	v_add_co_u32_e32 v96, vcc, 0x11401000, v94
	v_sub_f32_e32 v99, v67, v227
	v_sub_f32_e32 v98, v66, v226
	v_addc_co_u32_e32 v97, vcc, 0, v95, vcc
	v_pk_add_f32 v[82:83], v[82:83], v[98:99]
	v_add_co_u32_e32 v98, vcc, 0x11481000, v94
	s_nop 1
	v_addc_co_u32_e32 v99, vcc, 0, v95, vcc
	v_add_co_u32_e32 v100, vcc, 0x11402000, v94
	s_nop 1
	v_addc_co_u32_e32 v101, vcc, 0, v95, vcc
	v_add_co_u32_e32 v94, vcc, 0x11482000, v94
	s_nop 1
	v_addc_co_u32_e32 v95, vcc, 0, v95, vcc
	global_load_dwordx4 v[108:111], v[96:97], off
	global_load_dwordx4 v[104:107], v[98:99], off
	s_nop 0
	global_load_dwordx4 v[96:99], v[100:101], off
	s_nop 0
	global_load_dwordx4 v[100:103], v[94:95], off
	s_cbranch_scc1 .LBB0_1337
; template <int BUF>
; __device__ __forceinline__ void fox_tile(f32x16* o, float& m_reg, float& l_reg, const char* lds, const float* ckl, float* al_l, int vb0, const bf16x8* qr, float cq, int qpos, int kb0, bool need_mask, int r32, int hi) {
;     ...
;     if (need_mask) { const float NEG = -__builtin_inff(); const int dq = qpos - kb0 - 4 * hi;
; #pragma unroll
;         for (int r = 0; r < 16; ++r) { const int c = (r & 3) + 8 * (r >> 2); if (c > dq) p0[r] = NEG; if (c + 32 > dq) p1[r] = NEG; } }
	v_cmp_gt_i32_e64 s[68:69], 26, v161
	v_cmp_gt_i32_e64 s[70:71], 27, v161
	v_cmp_gt_i32_e64 s[66:67], 25, v161
	s_and_b64 s[68:69], s[70:71], s[68:69]
	v_cmp_gt_i32_e64 s[64:65], 24, v161
	s_and_b64 s[66:67], s[68:69], s[66:67]
	v_cmp_gt_i32_e64 s[62:63], 19, v161
	s_and_b64 s[64:65], s[66:67], s[64:65]
	v_cmp_gt_i32_e64 s[60:61], 18, v161
	s_and_b64 s[62:63], s[64:65], s[62:63]
	v_cmp_gt_i32_e64 s[58:59], 17, v161
	s_and_b64 s[60:61], s[62:63], s[60:61]
	v_cmp_gt_i32_e64 s[56:57], 16, v161
	s_and_b64 s[58:59], s[60:61], s[58:59]
	v_cmp_gt_i32_e64 s[54:55], 11, v161
	s_and_b64 s[56:57], s[58:59], s[56:57]
	v_cmp_gt_i32_e64 s[52:53], 10, v161
	s_and_b64 s[54:55], s[56:57], s[54:55]
	v_cmp_gt_i32_e64 s[50:51], 9, v161
	s_and_b64 s[52:53], s[54:55], s[52:53]
	v_cmp_gt_i32_e64 s[48:49], 8, v161
	s_and_b64 s[50:51], s[52:53], s[50:51]
	v_cmp_gt_i32_e64 s[46:47], 3, v161
	s_and_b64 s[48:49], s[50:51], s[48:49]
	v_cmp_gt_i32_e64 s[44:45], 2, v161
	s_and_b64 s[46:47], s[48:49], s[46:47]
	v_cmp_gt_i32_e64 s[42:43], 1, v161
	s_and_b64 s[44:45], s[46:47], s[44:45]
	v_cmp_gt_i32_e64 s[0:1], 0, v161
	s_and_b64 s[42:43], s[44:45], s[42:43]
	s_and_b64 s[0:1], s[42:43], s[0:1]
	v_cmp_gt_i32_e64 s[38:39], 58, v161
	v_cndmask_b32_e64 v136, v136, v143, s[0:1]
	v_cmp_gt_i32_e64 s[0:1], 59, v161
	v_cmp_gt_i32_e64 s[36:37], 57, v161
	v_cmp_gt_i32_e64 s[34:35], 56, v161
	v_cndmask_b32_e64 v81, v81, v143, s[0:1]
	s_and_b64 s[0:1], s[0:1], s[38:39]
	v_cndmask_b32_e64 v80, v80, v143, s[0:1]
	s_and_b64 s[0:1], s[0:1], s[36:37]
	v_cmp_gt_i32_e64 s[30:31], 51, v161
	v_cndmask_b32_e64 v93, v93, v143, s[0:1]
	s_and_b64 s[0:1], s[0:1], s[34:35]
	v_cmp_gt_i32_e64 s[28:29], 50, v161
	v_cndmask_b32_e64 v92, v92, v143, s[0:1]
	s_and_b64 s[0:1], s[0:1], s[30:31]
	v_cmp_gt_i32_e64 s[26:27], 49, v161
	v_cndmask_b32_e64 v91, v91, v143, s[0:1]
	s_and_b64 s[0:1], s[0:1], s[28:29]
	v_cmp_gt_i32_e64 s[24:25], 48, v161
	v_cndmask_b32_e64 v90, v90, v143, s[0:1]
	s_and_b64 s[0:1], s[0:1], s[26:27]
	v_cmp_gt_i32_e64 s[22:23], 43, v161
	v_cndmask_b32_e64 v89, v89, v143, s[0:1]
	s_and_b64 s[0:1], s[0:1], s[24:25]
	v_cmp_gt_i32_e64 s[20:21], 42, v161
	v_cndmask_b32_e64 v88, v88, v143, s[0:1]
	s_and_b64 s[0:1], s[0:1], s[22:23]
	v_cmp_gt_i32_e64 s[18:19], 41, v161
	v_cndmask_b32_e64 v87, v87, v143, s[0:1]
	s_and_b64 s[0:1], s[0:1], s[20:21]
	v_cmp_gt_i32_e64 s[16:17], 40, v161
	v_cndmask_b32_e64 v86, v86, v143, s[0:1]
	s_and_b64 s[0:1], s[0:1], s[18:19]
	v_cmp_gt_i32_e64 s[14:15], 35, v161
	v_cndmask_b32_e64 v85, v85, v143, s[0:1]
	s_and_b64 s[0:1], s[0:1], s[16:17]
	v_cmp_gt_i32_e64 s[12:13], 34, v161
	v_cndmask_b32_e64 v84, v84, v143, s[0:1]
	s_and_b64 s[0:1], s[0:1], s[14:15]
	v_cmp_gt_i32_e64 s[10:11], 33, v161
	v_cndmask_b32_e64 v83, v83, v143, s[0:1]
	s_and_b64 s[0:1], s[0:1], s[12:13]
	v_cmp_gt_i32_e32 vcc, 32, v161
	v_cndmask_b32_e64 v82, v82, v143, s[0:1]
	s_and_b64 s[0:1], s[0:1], s[10:11]
	s_and_b64 vcc, s[0:1], vcc
	v_cndmask_b32_e64 v121, v121, v143, s[70:71]
	v_cndmask_b32_e64 v120, v120, v143, s[68:69]
	v_cndmask_b32_e64 v123, v123, v143, s[66:67]
	v_cndmask_b32_e64 v122, v122, v143, s[64:65]
	v_cndmask_b32_e64 v125, v125, v143, s[62:63]
	v_cndmask_b32_e64 v124, v124, v143, s[60:61]
	v_cndmask_b32_e64 v127, v127, v143, s[58:59]
	v_cndmask_b32_e64 v126, v126, v143, s[56:57]
	v_cndmask_b32_e64 v131, v131, v143, s[54:55]
	v_cndmask_b32_e64 v130, v130, v143, s[52:53]
	v_cndmask_b32_e64 v133, v133, v143, s[50:51]
	v_cndmask_b32_e64 v132, v132, v143, s[48:49]
	v_cndmask_b32_e64 v135, v135, v143, s[46:47]
	v_cndmask_b32_e64 v134, v134, v143, s[44:45]
	v_cndmask_b32_e64 v137, v137, v143, s[42:43]
	v_cndmask_b32_e64 v139, v139, v143, s[0:1]
	v_cndmask_b32_e32 v138, v138, v143, vcc

; template <int KB>
; __device__ __forceinline__ void qkt(f32x16& p0, f32x16& p1, const char* K_lds, int r32, int hi, const bf16x8* qs) {
;     p0 = f32x16{}; p1 = f32x16{};
;     const char* kb[4];
; #pragma unroll
;     for (int dd = 0; dd < 4; ++dd) kb[dd] = K_lds + KB * SHM_K + KSWZ(r32, (dd * 16 + hi * 8) * 2);
; #pragma unroll
;     for (int d0 = 0; d0 < 8; ++d0) { const char* a = kb[d0 & 3] + (d0 >> 2) * 128;
;         bf16x8 b0 = *reinterpret_cast<const bf16x8*>(a);
;         bf16x8 b1 = *reinterpret_cast<const bf16x8*>(a + 32 * 256);
;         const bf16x8 qf = qs[d0 * 64];
;         p0 = __builtin_amdgcn_mfma_f32_32x32x16_bf16(b0, qf, p0, 0, 0, 0);
;         p1 = __builtin_amdgcn_mfma_f32_32x32x16_bf16(b1, qf, p1, 0, 0, 0); }
; template <int BUF>
; __device__ __forceinline__ void fox_tile(f32x16* o, float& m_reg, float& l_reg, const char* lds, const float* ckl, float* al_l, int vb0, const bf16x8* qr, float cq, int qpos, int kb0, bool need_mask, int r32, int hi) {
;     ...
;     const float* ck = ckl + kb0 + 4 * hi;
; #pragma unroll
;     for (int g = 0; g < 4; ++g) { const f32x4 c0 = *(const f32x4*)(ck + 8 * g), c1 = *(const f32x4*)(ck + 32 + 8 * g);
; #pragma unroll
;         for (int e = 0; e < 4; ++e) { p0[4 * g + e] += cq - c0[e]; p1[4 * g + e] += cq - c1[e]; } }
.LBB0_1343:
	s_cmp_le_i32 s72, s86
	ds_read_b128 v[232:235], v162 offset:32
	ds_read_b128 v[240:243], v162 offset:64
	ds_read_b128 v[244:247], v162 offset:96
	ds_read_b128 v[248:251], v162
	ds_read_b128 v[178:181], v152
	ds_read_b128 v[212:215], v163 offset:49152
	ds_read_b128 v[182:185], v152 offset:1024
	ds_read_b128 v[216:219], v164 offset:49152
	ds_read_b128 v[186:189], v152 offset:2048
	ds_read_b128 v[220:223], v165 offset:49152
	ds_read_b128 v[190:193], v152 offset:3072
	ds_read_b128 v[224:227], v166 offset:49152
	ds_read_b128 v[194:197], v152 offset:4096
	ds_read_b128 v[228:231], v163 offset:49280
	s_waitcnt lgkmcnt(10)
	v_sub_f32_e32 v133, v69, v233
	v_sub_f32_e32 v132, v68, v232
	v_sub_f32_e32 v131, v71, v235
	v_sub_f32_e32 v130, v70, v234
	v_sub_f32_e32 v127, v73, v241
	v_sub_f32_e32 v126, v72, v240
	v_sub_f32_e32 v125, v75, v243
	v_sub_f32_e32 v124, v74, v242
	v_sub_f32_e32 v135, v77, v245
	v_sub_f32_e32 v134, v76, v244
	v_sub_f32_e32 v139, v79, v247
	v_sub_f32_e32 v138, v78, v246
	v_sub_f32_e32 v211, v67, v251
	v_sub_f32_e32 v210, v66, v250
	v_sub_f32_e32 v137, v65, v249
	v_sub_f32_e32 v136, v64, v248
	s_waitcnt lgkmcnt(8)
	v_mfma_f32_32x32x16_bf16 v[80:95], v[212:215], v[178:181], 0
	ds_read_b128 v[198:201], v152 offset:5120
	ds_read_b128 v[232:235], v164 offset:49280
	s_waitcnt lgkmcnt(8)
	v_mfma_f32_32x32x16_bf16 v[80:95], v[216:219], v[182:185], v[80:95]
	ds_read_b128 v[202:205], v152 offset:6144
	ds_read_b128 v[240:243], v165 offset:49280
	s_waitcnt lgkmcnt(8)
	v_mfma_f32_32x32x16_bf16 v[80:95], v[220:223], v[186:189], v[80:95]
	ds_read_b128 v[206:209], v152 offset:7168
	ds_read_b128 v[244:247], v166 offset:49280
	s_waitcnt lgkmcnt(8)
	v_mfma_f32_32x32x16_bf16 v[80:95], v[224:227], v[190:193], v[80:95]
	s_waitcnt lgkmcnt(6)
	v_mfma_f32_32x32x16_bf16 v[80:95], v[228:231], v[194:197], v[80:95]
	s_waitcnt lgkmcnt(4)
	v_mfma_f32_32x32x16_bf16 v[80:95], v[232:235], v[198:201], v[80:95]
	s_waitcnt lgkmcnt(2)
	v_mfma_f32_32x32x16_bf16 v[80:95], v[240:243], v[202:205], v[80:95]
	s_waitcnt lgkmcnt(0)
	v_mfma_f32_32x32x16_bf16 v[80:95], v[244:247], v[206:209], v[80:95]
	ds_read_b128 v[212:215], v163 offset:57344
	ds_read_b128 v[216:219], v164 offset:57344
	ds_read_b128 v[220:223], v165 offset:57344
	ds_read_b128 v[224:227], v166 offset:57344
	ds_read_b128 v[228:231], v163 offset:57472
	ds_read_b128 v[232:235], v164 offset:57472
	ds_read_b128 v[240:243], v165 offset:57472
	ds_read_b128 v[244:247], v166 offset:57472
	s_nop 11
	v_pk_add_f32 v[136:137], v[80:81], v[136:137]
	v_pk_add_f32 v[122:123], v[92:93], v[134:135]
	v_pk_add_f32 v[134:135], v[82:83], v[210:211]
	v_pk_add_f32 v[120:121], v[94:95], v[138:139]
	v_pk_add_f32 v[124:125], v[90:91], v[124:125]
	v_pk_add_f32 v[126:127], v[88:89], v[126:127]
	v_pk_add_f32 v[130:131], v[86:87], v[130:131]
	v_pk_add_f32 v[132:133], v[84:85], v[132:133]
	s_waitcnt lgkmcnt(7)
	v_mfma_f32_32x32x16_bf16 v[80:95], v[212:215], v[178:181], 0
	s_waitcnt lgkmcnt(6)
	v_mfma_f32_32x32x16_bf16 v[80:95], v[216:219], v[182:185], v[80:95]
	s_waitcnt lgkmcnt(5)
	v_mfma_f32_32x32x16_bf16 v[80:95], v[220:223], v[186:189], v[80:95]
	s_waitcnt lgkmcnt(4)
	v_mfma_f32_32x32x16_bf16 v[80:95], v[224:227], v[190:193], v[80:95]
	ds_read_b128 v[212:215], v162 offset:160
	ds_read_b128 v[216:219], v162 offset:192
	ds_read_b128 v[220:223], v162 offset:224
	ds_read_b128 v[224:227], v162 offset:128
	s_waitcnt lgkmcnt(7)
	v_mfma_f32_32x32x16_bf16 v[80:95], v[228:231], v[194:197], v[80:95]
	s_waitcnt lgkmcnt(6)
	v_mfma_f32_32x32x16_bf16 v[80:95], v[232:235], v[198:201], v[80:95]
	s_waitcnt lgkmcnt(5)
	v_mfma_f32_32x32x16_bf16 v[80:95], v[240:243], v[202:205], v[80:95]
	s_waitcnt lgkmcnt(4)
	v_mfma_f32_32x32x16_bf16 v[80:95], v[244:247], v[206:209], v[80:95]
	s_nop 3
	s_waitcnt lgkmcnt(3)
	v_sub_f32_e32 v183, v69, v213
	v_sub_f32_e32 v182, v68, v212
	v_sub_f32_e32 v185, v71, v215
	v_sub_f32_e32 v184, v70, v214
	s_nop 4
	v_pk_add_f32 v[86:87], v[86:87], v[184:185]
	v_pk_add_f32 v[84:85], v[84:85], v[182:183]
	s_waitcnt lgkmcnt(2)
	v_sub_f32_e32 v187, v73, v217
	v_sub_f32_e32 v186, v72, v216
	v_sub_f32_e32 v189, v75, v219
	v_sub_f32_e32 v188, v74, v218
	v_pk_add_f32 v[90:91], v[90:91], v[188:189]
	v_pk_add_f32 v[88:89], v[88:89], v[186:187]
	s_waitcnt lgkmcnt(1)
	v_sub_f32_e32 v191, v77, v221
	v_sub_f32_e32 v190, v76, v220
	v_sub_f32_e32 v193, v79, v223
	v_sub_f32_e32 v192, v78, v222
	v_pk_add_f32 v[92:93], v[92:93], v[190:191]
	s_waitcnt lgkmcnt(0)
	v_sub_f32_e32 v181, v67, v227
	v_sub_f32_e32 v180, v66, v226
	v_sub_f32_e32 v139, v65, v225
	v_sub_f32_e32 v138, v64, v224
	v_pk_add_f32 v[138:139], v[80:81], v[138:139]
	v_pk_add_f32 v[80:81], v[94:95], v[192:193]
	v_pk_add_f32 v[82:83], v[82:83], v[180:181]
	s_cbranch_scc1 .LBB0_1345
; template <int BUF>
; __device__ __forceinline__ void fox_tile(f32x16* o, float& m_reg, float& l_reg, const char* lds, const float* ckl, float* al_l, int vb0, const bf16x8* qr, float cq, int qpos, int kb0, bool need_mask, int r32, int hi) {
;     ...
;     if (need_mask) { const float NEG = -__builtin_inff(); const int dq = qpos - kb0 - 4 * hi;
; #pragma unroll
;         for (int r = 0; r < 16; ++r) { const int c = (r & 3) + 8 * (r >> 2); if (c > dq) p0[r] = NEG; if (c + 32 > dq) p1[r] = NEG; } }
	v_add_u32_e32 v94, 64, v161
	v_cmp_gt_i32_e64 s[68:69], 26, v94
	v_cmp_gt_i32_e64 s[70:71], 27, v94
	v_cmp_gt_i32_e64 s[66:67], 25, v94
	s_and_b64 s[68:69], s[70:71], s[68:69]
	v_cmp_gt_i32_e64 s[64:65], 24, v94
	s_and_b64 s[66:67], s[68:69], s[66:67]
	v_cmp_gt_i32_e64 s[62:63], 19, v94
	s_and_b64 s[64:65], s[66:67], s[64:65]
	v_cmp_gt_i32_e64 s[60:61], 18, v94
	s_and_b64 s[62:63], s[64:65], s[62:63]
	v_cmp_gt_i32_e64 s[58:59], 17, v94
	s_and_b64 s[60:61], s[62:63], s[60:61]
	v_cmp_gt_i32_e64 s[56:57], 16, v94
	s_and_b64 s[58:59], s[60:61], s[58:59]
	v_cmp_gt_i32_e64 s[54:55], 11, v94
	s_and_b64 s[56:57], s[58:59], s[56:57]
	v_cmp_gt_i32_e64 s[52:53], 10, v94
	s_and_b64 s[54:55], s[56:57], s[54:55]
	v_cmp_gt_i32_e64 s[50:51], 9, v94
	s_and_b64 s[52:53], s[54:55], s[52:53]
	v_cmp_gt_i32_e64 s[48:49], 8, v94
	s_and_b64 s[50:51], s[52:53], s[50:51]
	v_cmp_gt_i32_e64 s[46:47], 3, v94
	s_and_b64 s[48:49], s[50:51], s[48:49]
	v_cmp_gt_i32_e64 s[44:45], 2, v94
	s_and_b64 s[46:47], s[48:49], s[46:47]
	v_cmp_gt_i32_e64 s[42:43], 1, v94
	s_and_b64 s[44:45], s[46:47], s[44:45]
	v_cmp_gt_i32_e64 s[0:1], 0, v94
	s_and_b64 s[42:43], s[44:45], s[42:43]
	s_and_b64 s[0:1], s[42:43], s[0:1]
	v_cmp_gt_i32_e64 s[38:39], 58, v94
	v_cndmask_b32_e64 v136, v136, v143, s[0:1]
	v_cmp_gt_i32_e64 s[0:1], 59, v94
	v_cmp_gt_i32_e64 s[36:37], 57, v94
	v_cmp_gt_i32_e64 s[34:35], 56, v94
	v_cndmask_b32_e64 v81, v81, v143, s[0:1]
	s_and_b64 s[0:1], s[0:1], s[38:39]
	v_cndmask_b32_e64 v80, v80, v143, s[0:1]
	s_and_b64 s[0:1], s[0:1], s[36:37]
	v_cmp_gt_i32_e64 s[30:31], 51, v94
	v_cndmask_b32_e64 v93, v93, v143, s[0:1]
	s_and_b64 s[0:1], s[0:1], s[34:35]
	v_cmp_gt_i32_e64 s[28:29], 50, v94
	v_cndmask_b32_e64 v92, v92, v143, s[0:1]
	s_and_b64 s[0:1], s[0:1], s[30:31]
	v_cmp_gt_i32_e64 s[26:27], 49, v94
	v_cndmask_b32_e64 v91, v91, v143, s[0:1]
	s_and_b64 s[0:1], s[0:1], s[28:29]
	v_cmp_gt_i32_e64 s[24:25], 48, v94
	v_cndmask_b32_e64 v90, v90, v143, s[0:1]
	s_and_b64 s[0:1], s[0:1], s[26:27]
	v_cmp_gt_i32_e64 s[22:23], 43, v94
	v_cndmask_b32_e64 v89, v89, v143, s[0:1]
	s_and_b64 s[0:1], s[0:1], s[24:25]
	v_cmp_gt_i32_e64 s[20:21], 42, v94
	v_cndmask_b32_e64 v88, v88, v143, s[0:1]
	s_and_b64 s[0:1], s[0:1], s[22:23]
	v_cmp_gt_i32_e64 s[18:19], 41, v94
	v_cndmask_b32_e64 v87, v87, v143, s[0:1]
	s_and_b64 s[0:1], s[0:1], s[20:21]
	v_cmp_gt_i32_e64 s[16:17], 40, v94
	v_cndmask_b32_e64 v86, v86, v143, s[0:1]
	s_and_b64 s[0:1], s[0:1], s[18:19]
	v_cmp_gt_i32_e64 s[14:15], 35, v94
	v_cndmask_b32_e64 v85, v85, v143, s[0:1]
	s_and_b64 s[0:1], s[0:1], s[16:17]
	v_cmp_gt_i32_e64 s[12:13], 34, v94
	v_cndmask_b32_e64 v84, v84, v143, s[0:1]
	s_and_b64 s[0:1], s[0:1], s[14:15]
	v_cmp_gt_i32_e64 s[10:11], 33, v94
	v_cndmask_b32_e64 v83, v83, v143, s[0:1]
	s_and_b64 s[0:1], s[0:1], s[12:13]
	v_cmp_gt_i32_e32 vcc, 32, v94
	v_cndmask_b32_e64 v82, v82, v143, s[0:1]
	s_and_b64 s[0:1], s[0:1], s[10:11]
	s_and_b64 vcc, s[0:1], vcc
	v_cndmask_b32_e64 v121, v121, v143, s[70:71]
	v_cndmask_b32_e64 v120, v120, v143, s[68:69]
	v_cndmask_b32_e64 v123, v123, v143, s[66:67]
	v_cndmask_b32_e64 v122, v122, v143, s[64:65]
	v_cndmask_b32_e64 v125, v125, v143, s[62:63]
	v_cndmask_b32_e64 v124, v124, v143, s[60:61]
	v_cndmask_b32_e64 v127, v127, v143, s[58:59]
	v_cndmask_b32_e64 v126, v126, v143, s[56:57]
	v_cndmask_b32_e64 v131, v131, v143, s[54:55]
	v_cndmask_b32_e64 v130, v130, v143, s[52:53]
	v_cndmask_b32_e64 v133, v133, v143, s[50:51]
	v_cndmask_b32_e64 v132, v132, v143, s[48:49]
	v_cndmask_b32_e64 v135, v135, v143, s[46:47]
	v_cndmask_b32_e64 v134, v134, v143, s[44:45]
	v_cndmask_b32_e64 v137, v137, v143, s[42:43]
	v_cndmask_b32_e64 v139, v139, v143, s[0:1]
	v_cndmask_b32_e32 v138, v138, v143, vcc

; template <int KB>
; __device__ __forceinline__ void qkt(f32x16& p0, f32x16& p1, const char* K_lds, int r32, int hi, const bf16x8* qs) {
;     p0 = f32x16{}; p1 = f32x16{};
;     const char* kb[4];
; #pragma unroll
;     for (int dd = 0; dd < 4; ++dd) kb[dd] = K_lds + KB * SHM_K + KSWZ(r32, (dd * 16 + hi * 8) * 2);
; #pragma unroll
;     for (int d0 = 0; d0 < 8; ++d0) { const char* a = kb[d0 & 3] + (d0 >> 2) * 128;
;         bf16x8 b0 = *reinterpret_cast<const bf16x8*>(a);
;         bf16x8 b1 = *reinterpret_cast<const bf16x8*>(a + 32 * 256);
;         const bf16x8 qf = qs[d0 * 64];
;         p0 = __builtin_amdgcn_mfma_f32_32x32x16_bf16(b0, qf, p0, 0, 0, 0);
;         p1 = __builtin_amdgcn_mfma_f32_32x32x16_bf16(b1, qf, p1, 0, 0, 0); }
; template <int BUF>
; __device__ __forceinline__ void fox_tile(f32x16* o, float& m_reg, float& l_reg, const char* lds, const float* ckl, float* al_l, int vb0, const bf16x8* qr, float cq, int qpos, int kb0, bool need_mask, int r32, int hi) {
;     ...
;     const float* ck = ckl + kb0 + 4 * hi;
; #pragma unroll
;     for (int g = 0; g < 4; ++g) { const f32x4 c0 = *(const f32x4*)(ck + 8 * g), c1 = *(const f32x4*)(ck + 32 + 8 * g);
; #pragma unroll
;         for (int e = 0; e < 4; ++e) { p0[4 * g + e] += cq - c0[e]; p1[4 * g + e] += cq - c1[e]; } }
.LBB0_1366:
	s_add_i32 s0, s79, 63
	s_cmp_le_i32 s0, s73
	s_waitcnt vmcnt(0)
	ds_read_b128 v[232:235], v161 offset:288
	ds_read_b128 v[240:243], v161 offset:320
	ds_read_b128 v[244:247], v161 offset:352
	ds_read_b128 v[248:251], v161 offset:256
	ds_read_b128 v[96:99], v148
	ds_read_b128 v[212:215], v162 offset:32768
	ds_read_b128 v[104:107], v148 offset:1024
	ds_read_b128 v[216:219], v163 offset:32768
	ds_read_b128 v[108:111], v148 offset:2048
	ds_read_b128 v[220:223], v164 offset:32768
	ds_read_b128 v[166:169], v148 offset:3072
	ds_read_b128 v[224:227], v165 offset:32768
	ds_read_b128 v[178:181], v148 offset:4096
	ds_read_b128 v[228:231], v162 offset:32896
	s_waitcnt lgkmcnt(10)
	v_sub_f32_e32 v133, v69, v233
	v_sub_f32_e32 v132, v68, v232
	v_sub_f32_e32 v131, v71, v235
	v_sub_f32_e32 v130, v70, v234
	v_sub_f32_e32 v127, v73, v241
	v_sub_f32_e32 v126, v72, v240
	v_sub_f32_e32 v125, v75, v243
	v_sub_f32_e32 v124, v74, v242
	v_sub_f32_e32 v123, v77, v245
	v_sub_f32_e32 v122, v76, v244
	v_sub_f32_e32 v121, v79, v247
	v_sub_f32_e32 v120, v78, v246
	v_sub_f32_e32 v135, v67, v251
	v_sub_f32_e32 v134, v66, v250
	v_sub_f32_e32 v137, v65, v249
	v_sub_f32_e32 v136, v64, v248
	s_waitcnt lgkmcnt(8)
	v_mfma_f32_32x32x16_bf16 v[80:95], v[212:215], v[96:99], 0
	ds_read_b128 v[182:185], v148 offset:5120
	ds_read_b128 v[232:235], v163 offset:32896
	s_waitcnt lgkmcnt(8)
	v_mfma_f32_32x32x16_bf16 v[80:95], v[216:219], v[104:107], v[80:95]
	ds_read_b128 v[186:189], v148 offset:6144
	ds_read_b128 v[240:243], v164 offset:32896
	s_waitcnt lgkmcnt(8)
	v_mfma_f32_32x32x16_bf16 v[80:95], v[220:223], v[108:111], v[80:95]
	ds_read_b128 v[190:193], v148 offset:7168
	ds_read_b128 v[244:247], v165 offset:32896
	s_waitcnt lgkmcnt(8)
	v_mfma_f32_32x32x16_bf16 v[80:95], v[224:227], v[166:169], v[80:95]
	s_waitcnt lgkmcnt(6)
	v_mfma_f32_32x32x16_bf16 v[80:95], v[228:231], v[178:181], v[80:95]
	s_waitcnt lgkmcnt(4)
	v_mfma_f32_32x32x16_bf16 v[80:95], v[232:235], v[182:185], v[80:95]
	s_waitcnt lgkmcnt(2)
	v_mfma_f32_32x32x16_bf16 v[80:95], v[240:243], v[186:189], v[80:95]
	s_waitcnt lgkmcnt(0)
	v_mfma_f32_32x32x16_bf16 v[80:95], v[244:247], v[190:193], v[80:95]
	ds_read_b128 v[212:215], v162 offset:40960
	ds_read_b128 v[216:219], v163 offset:40960
	ds_read_b128 v[220:223], v164 offset:40960
	ds_read_b128 v[224:227], v165 offset:40960
	ds_read_b128 v[228:231], v162 offset:41088
	ds_read_b128 v[232:235], v163 offset:41088
	ds_read_b128 v[240:243], v164 offset:41088
	ds_read_b128 v[244:247], v165 offset:41088
	s_nop 11
	v_pk_add_f32 v[136:137], v[80:81], v[136:137]
	v_pk_add_f32 v[134:135], v[82:83], v[134:135]
	v_pk_add_f32 v[120:121], v[94:95], v[120:121]
	v_pk_add_f32 v[122:123], v[92:93], v[122:123]
	v_pk_add_f32 v[124:125], v[90:91], v[124:125]
	v_pk_add_f32 v[126:127], v[88:89], v[126:127]
	v_pk_add_f32 v[130:131], v[86:87], v[130:131]
	v_pk_add_f32 v[132:133], v[84:85], v[132:133]
	s_waitcnt lgkmcnt(7)
	v_mfma_f32_32x32x16_bf16 v[80:95], v[212:215], v[96:99], 0
	s_waitcnt lgkmcnt(6)
	v_mfma_f32_32x32x16_bf16 v[80:95], v[216:219], v[104:107], v[80:95]
	s_waitcnt lgkmcnt(5)
	v_mfma_f32_32x32x16_bf16 v[80:95], v[220:223], v[108:111], v[80:95]
	s_waitcnt lgkmcnt(4)
	v_mfma_f32_32x32x16_bf16 v[80:95], v[224:227], v[166:169], v[80:95]
	ds_read_b128 v[212:215], v161 offset:416
	ds_read_b128 v[216:219], v161 offset:448
	ds_read_b128 v[220:223], v161 offset:480
	ds_read_b128 v[224:227], v161 offset:384
	s_waitcnt lgkmcnt(7)
	v_mfma_f32_32x32x16_bf16 v[80:95], v[228:231], v[178:181], v[80:95]
	s_waitcnt lgkmcnt(6)
	v_mfma_f32_32x32x16_bf16 v[80:95], v[232:235], v[182:185], v[80:95]
	s_waitcnt lgkmcnt(5)
	v_mfma_f32_32x32x16_bf16 v[80:95], v[240:243], v[186:189], v[80:95]
	s_waitcnt lgkmcnt(4)
	v_mfma_f32_32x32x16_bf16 v[80:95], v[244:247], v[190:193], v[80:95]
	s_nop 3
	s_waitcnt lgkmcnt(3)
	v_sub_f32_e32 v101, v69, v213
	v_sub_f32_e32 v100, v68, v212
	v_sub_f32_e32 v103, v71, v215
	v_sub_f32_e32 v102, v70, v214
	s_nop 4
	v_pk_add_f32 v[84:85], v[84:85], v[100:101]
	v_pk_add_f32 v[86:87], v[86:87], v[102:103]
	s_waitcnt lgkmcnt(2)
	v_sub_f32_e32 v105, v73, v217
	v_sub_f32_e32 v104, v72, v216
	v_sub_f32_e32 v107, v75, v219
	v_sub_f32_e32 v106, v74, v218
	v_pk_add_f32 v[90:91], v[90:91], v[106:107]
	v_pk_add_f32 v[88:89], v[88:89], v[104:105]
	s_waitcnt lgkmcnt(1)
	v_sub_f32_e32 v109, v77, v221
	v_sub_f32_e32 v108, v76, v220
	v_sub_f32_e32 v111, v79, v223
	v_sub_f32_e32 v110, v78, v222
	v_pk_add_f32 v[92:93], v[92:93], v[108:109]
	s_waitcnt lgkmcnt(0)
	v_sub_f32_e32 v97, v65, v225
	v_sub_f32_e32 v96, v64, v224
	v_pk_add_f32 v[138:139], v[80:81], v[96:97]
	v_pk_add_f32 v[80:81], v[94:95], v[110:111]
	v_lshl_add_u64 v[94:95], v[118:119], 0, v[112:113]
	v_add_co_u32_e32 v96, vcc, 0x11401000, v94
	v_sub_f32_e32 v99, v67, v227
	v_sub_f32_e32 v98, v66, v226
	v_addc_co_u32_e32 v97, vcc, 0, v95, vcc
	v_pk_add_f32 v[82:83], v[82:83], v[98:99]
	v_add_co_u32_e32 v98, vcc, 0x11481000, v94
	s_nop 1
	v_addc_co_u32_e32 v99, vcc, 0, v95, vcc
	v_add_co_u32_e32 v100, vcc, 0x11402000, v94
	s_nop 1
	v_addc_co_u32_e32 v101, vcc, 0, v95, vcc
	v_add_co_u32_e32 v94, vcc, 0x11482000, v94
	s_nop 1
	v_addc_co_u32_e32 v95, vcc, 0, v95, vcc
	global_load_dwordx4 v[108:111], v[96:97], off
	global_load_dwordx4 v[104:107], v[98:99], off
	s_nop 0
	global_load_dwordx4 v[96:99], v[100:101], off
	s_nop 0
	global_load_dwordx4 v[100:103], v[94:95], off
	s_cbranch_scc1 .LBB0_1368
; template <int BUF>
; __device__ __forceinline__ void fox_tile(f32x16* o, float& m_reg, float& l_reg, const char* lds, const float* ckl, float* al_l, int vb0, const bf16x8* qr, float cq, int qpos, int kb0, bool need_mask, int r32, int hi) {
;     ...
;     if (need_mask) { const float NEG = -__builtin_inff(); const int dq = qpos - kb0 - 4 * hi;
; #pragma unroll
;         for (int r = 0; r < 16; ++r) { const int c = (r & 3) + 8 * (r >> 2); if (c > dq) p0[r] = NEG; if (c + 32 > dq) p1[r] = NEG; } }
	v_cmp_gt_i32_e64 s[68:69], 26, v160
	v_cmp_gt_i32_e64 s[70:71], 27, v160
	v_cmp_gt_i32_e64 s[66:67], 25, v160
	s_and_b64 s[68:69], s[70:71], s[68:69]
	v_cmp_gt_i32_e64 s[64:65], 24, v160
	s_and_b64 s[66:67], s[68:69], s[66:67]
	v_cmp_gt_i32_e64 s[62:63], 19, v160
	s_and_b64 s[64:65], s[66:67], s[64:65]
	v_cmp_gt_i32_e64 s[60:61], 18, v160
	s_and_b64 s[62:63], s[64:65], s[62:63]
	v_cmp_gt_i32_e64 s[58:59], 17, v160
	s_and_b64 s[60:61], s[62:63], s[60:61]
	v_cmp_gt_i32_e64 s[56:57], 16, v160
	s_and_b64 s[58:59], s[60:61], s[58:59]
	v_cmp_gt_i32_e64 s[54:55], 11, v160
	s_and_b64 s[56:57], s[58:59], s[56:57]
	v_cmp_gt_i32_e64 s[52:53], 10, v160
	s_and_b64 s[54:55], s[56:57], s[54:55]
	v_cmp_gt_i32_e64 s[50:51], 9, v160
	s_and_b64 s[52:53], s[54:55], s[52:53]
	v_cmp_gt_i32_e64 s[48:49], 8, v160
	s_and_b64 s[50:51], s[52:53], s[50:51]
	v_cmp_gt_i32_e64 s[46:47], 3, v160
	s_and_b64 s[48:49], s[50:51], s[48:49]
	v_cmp_gt_i32_e64 s[44:45], 2, v160
	s_and_b64 s[46:47], s[48:49], s[46:47]
	v_cmp_gt_i32_e64 s[42:43], 1, v160
	s_and_b64 s[44:45], s[46:47], s[44:45]
	v_cmp_gt_i32_e64 s[0:1], 0, v160
	s_and_b64 s[42:43], s[44:45], s[42:43]
	s_and_b64 s[0:1], s[42:43], s[0:1]
	v_cmp_gt_i32_e64 s[38:39], 58, v160
	v_cndmask_b32_e64 v136, v136, v143, s[0:1]
	v_cmp_gt_i32_e64 s[0:1], 59, v160
	v_cmp_gt_i32_e64 s[36:37], 57, v160
	v_cmp_gt_i32_e64 s[34:35], 56, v160
	v_cndmask_b32_e64 v81, v81, v143, s[0:1]
	s_and_b64 s[0:1], s[0:1], s[38:39]
	v_cndmask_b32_e64 v80, v80, v143, s[0:1]
	s_and_b64 s[0:1], s[0:1], s[36:37]
	v_cmp_gt_i32_e64 s[30:31], 51, v160
	v_cndmask_b32_e64 v93, v93, v143, s[0:1]
	s_and_b64 s[0:1], s[0:1], s[34:35]
	v_cmp_gt_i32_e64 s[28:29], 50, v160
	v_cndmask_b32_e64 v92, v92, v143, s[0:1]
	s_and_b64 s[0:1], s[0:1], s[30:31]
	v_cmp_gt_i32_e64 s[26:27], 49, v160
	v_cndmask_b32_e64 v91, v91, v143, s[0:1]
	s_and_b64 s[0:1], s[0:1], s[28:29]
	v_cmp_gt_i32_e64 s[24:25], 48, v160
	v_cndmask_b32_e64 v90, v90, v143, s[0:1]
	s_and_b64 s[0:1], s[0:1], s[26:27]
	v_cmp_gt_i32_e64 s[22:23], 43, v160
	v_cndmask_b32_e64 v89, v89, v143, s[0:1]
	s_and_b64 s[0:1], s[0:1], s[24:25]
	v_cmp_gt_i32_e64 s[20:21], 42, v160
	v_cndmask_b32_e64 v88, v88, v143, s[0:1]
	s_and_b64 s[0:1], s[0:1], s[22:23]
	v_cmp_gt_i32_e64 s[18:19], 41, v160
	v_cndmask_b32_e64 v87, v87, v143, s[0:1]
	s_and_b64 s[0:1], s[0:1], s[20:21]
	v_cmp_gt_i32_e64 s[16:17], 40, v160
	v_cndmask_b32_e64 v86, v86, v143, s[0:1]
	s_and_b64 s[0:1], s[0:1], s[18:19]
	v_cmp_gt_i32_e64 s[14:15], 35, v160
	v_cndmask_b32_e64 v85, v85, v143, s[0:1]
	s_and_b64 s[0:1], s[0:1], s[16:17]
	v_cmp_gt_i32_e64 s[12:13], 34, v160
	v_cndmask_b32_e64 v84, v84, v143, s[0:1]
	s_and_b64 s[0:1], s[0:1], s[14:15]
	v_cmp_gt_i32_e64 s[10:11], 33, v160
	v_cndmask_b32_e64 v83, v83, v143, s[0:1]
	s_and_b64 s[0:1], s[0:1], s[12:13]
	v_cmp_gt_i32_e32 vcc, 32, v160
	v_cndmask_b32_e64 v82, v82, v143, s[0:1]
	s_and_b64 s[0:1], s[0:1], s[10:11]
	s_and_b64 vcc, s[0:1], vcc
	v_cndmask_b32_e64 v121, v121, v143, s[70:71]
	v_cndmask_b32_e64 v120, v120, v143, s[68:69]
	v_cndmask_b32_e64 v123, v123, v143, s[66:67]
	v_cndmask_b32_e64 v122, v122, v143, s[64:65]
	v_cndmask_b32_e64 v125, v125, v143, s[62:63]
	v_cndmask_b32_e64 v124, v124, v143, s[60:61]
	v_cndmask_b32_e64 v127, v127, v143, s[58:59]
	v_cndmask_b32_e64 v126, v126, v143, s[56:57]
	v_cndmask_b32_e64 v131, v131, v143, s[54:55]
	v_cndmask_b32_e64 v130, v130, v143, s[52:53]
	v_cndmask_b32_e64 v133, v133, v143, s[50:51]
	v_cndmask_b32_e64 v132, v132, v143, s[48:49]
	v_cndmask_b32_e64 v135, v135, v143, s[46:47]
	v_cndmask_b32_e64 v134, v134, v143, s[44:45]
	v_cndmask_b32_e64 v137, v137, v143, s[42:43]
	v_cndmask_b32_e64 v139, v139, v143, s[0:1]
	v_cndmask_b32_e32 v138, v138, v143, vcc

; template <int KB>
; __device__ __forceinline__ void qkt(f32x16& p0, f32x16& p1, const char* K_lds, int r32, int hi, const bf16x8* qs) {
;     p0 = f32x16{}; p1 = f32x16{};
;     const char* kb[4];
; #pragma unroll
;     for (int dd = 0; dd < 4; ++dd) kb[dd] = K_lds + KB * SHM_K + KSWZ(r32, (dd * 16 + hi * 8) * 2);
; #pragma unroll
;     for (int d0 = 0; d0 < 8; ++d0) { const char* a = kb[d0 & 3] + (d0 >> 2) * 128;
;         bf16x8 b0 = *reinterpret_cast<const bf16x8*>(a);
;         bf16x8 b1 = *reinterpret_cast<const bf16x8*>(a + 32 * 256);
;         const bf16x8 qf = qs[d0 * 64];
;         p0 = __builtin_amdgcn_mfma_f32_32x32x16_bf16(b0, qf, p0, 0, 0, 0);
;         p1 = __builtin_amdgcn_mfma_f32_32x32x16_bf16(b1, qf, p1, 0, 0, 0); }
; template <int BUF>
; __device__ __forceinline__ void fox_tile(f32x16* o, float& m_reg, float& l_reg, const char* lds, const float* ckl, float* al_l, int vb0, const bf16x8* qr, float cq, int qpos, int kb0, bool need_mask, int r32, int hi) {
;     ...
;     const float* ck = ckl + kb0 + 4 * hi;
; #pragma unroll
;     for (int g = 0; g < 4; ++g) { const f32x4 c0 = *(const f32x4*)(ck + 8 * g), c1 = *(const f32x4*)(ck + 32 + 8 * g);
; #pragma unroll
;         for (int e = 0; e < 4; ++e) { p0[4 * g + e] += cq - c0[e]; p1[4 * g + e] += cq - c1[e]; } }
.LBB0_1374:
	s_cmp_le_i32 s79, s82
	ds_read_b128 v[232:235], v161 offset:32
	ds_read_b128 v[240:243], v161 offset:64
	ds_read_b128 v[244:247], v161 offset:96
	ds_read_b128 v[248:251], v161
	ds_read_b128 v[178:181], v148
	ds_read_b128 v[212:215], v162 offset:49152
	ds_read_b128 v[182:185], v148 offset:1024
	ds_read_b128 v[216:219], v163 offset:49152
	ds_read_b128 v[186:189], v148 offset:2048
	ds_read_b128 v[220:223], v164 offset:49152
	ds_read_b128 v[190:193], v148 offset:3072
	ds_read_b128 v[224:227], v165 offset:49152
	ds_read_b128 v[194:197], v148 offset:4096
	ds_read_b128 v[228:231], v162 offset:49280
	s_waitcnt lgkmcnt(10)
	v_sub_f32_e32 v133, v69, v233
	v_sub_f32_e32 v132, v68, v232
	v_sub_f32_e32 v131, v71, v235
	v_sub_f32_e32 v130, v70, v234
	v_sub_f32_e32 v127, v73, v241
	v_sub_f32_e32 v126, v72, v240
	v_sub_f32_e32 v125, v75, v243
	v_sub_f32_e32 v124, v74, v242
	v_sub_f32_e32 v135, v77, v245
	v_sub_f32_e32 v134, v76, v244
	v_sub_f32_e32 v139, v79, v247
	v_sub_f32_e32 v138, v78, v246
	v_sub_f32_e32 v171, v67, v251
	v_sub_f32_e32 v170, v66, v250
	v_sub_f32_e32 v137, v65, v249
	v_sub_f32_e32 v136, v64, v248
	s_waitcnt lgkmcnt(8)
	v_mfma_f32_32x32x16_bf16 v[80:95], v[212:215], v[178:181], 0
	ds_read_b128 v[198:201], v148 offset:5120
	ds_read_b128 v[232:235], v163 offset:49280
	s_waitcnt lgkmcnt(8)
	v_mfma_f32_32x32x16_bf16 v[80:95], v[216:219], v[182:185], v[80:95]
	ds_read_b128 v[202:205], v148 offset:6144
	ds_read_b128 v[240:243], v164 offset:49280
	s_waitcnt lgkmcnt(8)
	v_mfma_f32_32x32x16_bf16 v[80:95], v[220:223], v[186:189], v[80:95]
	ds_read_b128 v[206:209], v148 offset:7168
	ds_read_b128 v[244:247], v165 offset:49280
	s_waitcnt lgkmcnt(8)
	v_mfma_f32_32x32x16_bf16 v[80:95], v[224:227], v[190:193], v[80:95]
	s_waitcnt lgkmcnt(6)
	v_mfma_f32_32x32x16_bf16 v[80:95], v[228:231], v[194:197], v[80:95]
	s_waitcnt lgkmcnt(4)
	v_mfma_f32_32x32x16_bf16 v[80:95], v[232:235], v[198:201], v[80:95]
	s_waitcnt lgkmcnt(2)
	v_mfma_f32_32x32x16_bf16 v[80:95], v[240:243], v[202:205], v[80:95]
	s_waitcnt lgkmcnt(0)
	v_mfma_f32_32x32x16_bf16 v[80:95], v[244:247], v[206:209], v[80:95]
	ds_read_b128 v[212:215], v162 offset:57344
	ds_read_b128 v[216:219], v163 offset:57344
	ds_read_b128 v[220:223], v164 offset:57344
	ds_read_b128 v[224:227], v165 offset:57344
	ds_read_b128 v[228:231], v162 offset:57472
	ds_read_b128 v[232:235], v163 offset:57472
	ds_read_b128 v[240:243], v164 offset:57472
	ds_read_b128 v[244:247], v165 offset:57472
	s_nop 11
	v_pk_add_f32 v[136:137], v[80:81], v[136:137]
	v_pk_add_f32 v[122:123], v[92:93], v[134:135]
	v_pk_add_f32 v[134:135], v[82:83], v[170:171]
	v_pk_add_f32 v[120:121], v[94:95], v[138:139]
	v_pk_add_f32 v[124:125], v[90:91], v[124:125]
	v_pk_add_f32 v[126:127], v[88:89], v[126:127]
	v_pk_add_f32 v[130:131], v[86:87], v[130:131]
	v_pk_add_f32 v[132:133], v[84:85], v[132:133]
	s_waitcnt lgkmcnt(7)
	v_mfma_f32_32x32x16_bf16 v[80:95], v[212:215], v[178:181], 0
	s_waitcnt lgkmcnt(6)
	v_mfma_f32_32x32x16_bf16 v[80:95], v[216:219], v[182:185], v[80:95]
	s_waitcnt lgkmcnt(5)
	v_mfma_f32_32x32x16_bf16 v[80:95], v[220:223], v[186:189], v[80:95]
	s_waitcnt lgkmcnt(4)
	v_mfma_f32_32x32x16_bf16 v[80:95], v[224:227], v[190:193], v[80:95]
	ds_read_b128 v[212:215], v161 offset:160
	ds_read_b128 v[216:219], v161 offset:192
	ds_read_b128 v[220:223], v161 offset:224
	ds_read_b128 v[224:227], v161 offset:128
	s_waitcnt lgkmcnt(7)
	v_mfma_f32_32x32x16_bf16 v[80:95], v[228:231], v[194:197], v[80:95]
	s_waitcnt lgkmcnt(6)
	v_mfma_f32_32x32x16_bf16 v[80:95], v[232:235], v[198:201], v[80:95]
	s_waitcnt lgkmcnt(5)
	v_mfma_f32_32x32x16_bf16 v[80:95], v[240:243], v[202:205], v[80:95]
	s_waitcnt lgkmcnt(4)
	v_mfma_f32_32x32x16_bf16 v[80:95], v[244:247], v[206:209], v[80:95]
	s_nop 3
	s_waitcnt lgkmcnt(3)
	v_sub_f32_e32 v171, v69, v213
	v_sub_f32_e32 v170, v68, v212
	v_sub_f32_e32 v183, v71, v215
	v_sub_f32_e32 v182, v70, v214
	s_nop 4
	v_pk_add_f32 v[86:87], v[86:87], v[182:183]
	v_pk_add_f32 v[84:85], v[84:85], v[170:171]
	s_waitcnt lgkmcnt(2)
	v_sub_f32_e32 v185, v73, v217
	v_sub_f32_e32 v184, v72, v216
	v_sub_f32_e32 v187, v75, v219
	v_sub_f32_e32 v186, v74, v218
	v_pk_add_f32 v[90:91], v[90:91], v[186:187]
	v_pk_add_f32 v[88:89], v[88:89], v[184:185]
	s_waitcnt lgkmcnt(1)
	v_sub_f32_e32 v189, v77, v221
	v_sub_f32_e32 v188, v76, v220
	v_sub_f32_e32 v191, v79, v223
	v_sub_f32_e32 v190, v78, v222
	v_pk_add_f32 v[92:93], v[92:93], v[188:189]
	s_waitcnt lgkmcnt(0)
	v_sub_f32_e32 v181, v67, v227
	v_sub_f32_e32 v180, v66, v226
	v_sub_f32_e32 v139, v65, v225
	v_sub_f32_e32 v138, v64, v224
	v_pk_add_f32 v[138:139], v[80:81], v[138:139]
	v_pk_add_f32 v[80:81], v[94:95], v[190:191]
	v_pk_add_f32 v[82:83], v[82:83], v[180:181]
	s_cbranch_scc1 .LBB0_1376
; template <int BUF>
; __device__ __forceinline__ void fox_tile(f32x16* o, float& m_reg, float& l_reg, const char* lds, const float* ckl, float* al_l, int vb0, const bf16x8* qr, float cq, int qpos, int kb0, bool need_mask, int r32, int hi) {
;     ...
;     if (need_mask) { const float NEG = -__builtin_inff(); const int dq = qpos - kb0 - 4 * hi;
; #pragma unroll
;         for (int r = 0; r < 16; ++r) { const int c = (r & 3) + 8 * (r >> 2); if (c > dq) p0[r] = NEG; if (c + 32 > dq) p1[r] = NEG; } }
	v_add_u32_e32 v94, 64, v160
	v_cmp_gt_i32_e64 s[68:69], 26, v94
	v_cmp_gt_i32_e64 s[70:71], 27, v94
	v_cmp_gt_i32_e64 s[66:67], 25, v94
	s_and_b64 s[68:69], s[70:71], s[68:69]
	v_cmp_gt_i32_e64 s[64:65], 24, v94
	s_and_b64 s[66:67], s[68:69], s[66:67]
	v_cmp_gt_i32_e64 s[62:63], 19, v94
	s_and_b64 s[64:65], s[66:67], s[64:65]
	v_cmp_gt_i32_e64 s[60:61], 18, v94
	s_and_b64 s[62:63], s[64:65], s[62:63]
	v_cmp_gt_i32_e64 s[58:59], 17, v94
	s_and_b64 s[60:61], s[62:63], s[60:61]
	v_cmp_gt_i32_e64 s[56:57], 16, v94
	s_and_b64 s[58:59], s[60:61], s[58:59]
	v_cmp_gt_i32_e64 s[54:55], 11, v94
	s_and_b64 s[56:57], s[58:59], s[56:57]
	v_cmp_gt_i32_e64 s[52:53], 10, v94
	s_and_b64 s[54:55], s[56:57], s[54:55]
	v_cmp_gt_i32_e64 s[50:51], 9, v94
	s_and_b64 s[52:53], s[54:55], s[52:53]
	v_cmp_gt_i32_e64 s[48:49], 8, v94
	s_and_b64 s[50:51], s[52:53], s[50:51]
	v_cmp_gt_i32_e64 s[46:47], 3, v94
	s_and_b64 s[48:49], s[50:51], s[48:49]
	v_cmp_gt_i32_e64 s[44:45], 2, v94
	s_and_b64 s[46:47], s[48:49], s[46:47]
	v_cmp_gt_i32_e64 s[42:43], 1, v94
	s_and_b64 s[44:45], s[46:47], s[44:45]
	v_cmp_gt_i32_e64 s[0:1], 0, v94
	s_and_b64 s[42:43], s[44:45], s[42:43]
	s_and_b64 s[0:1], s[42:43], s[0:1]
	v_cmp_gt_i32_e64 s[38:39], 58, v94
	v_cndmask_b32_e64 v136, v136, v143, s[0:1]
	v_cmp_gt_i32_e64 s[0:1], 59, v94
	v_cmp_gt_i32_e64 s[36:37], 57, v94
	v_cmp_gt_i32_e64 s[34:35], 56, v94
	v_cndmask_b32_e64 v81, v81, v143, s[0:1]
	s_and_b64 s[0:1], s[0:1], s[38:39]
	v_cndmask_b32_e64 v80, v80, v143, s[0:1]
	s_and_b64 s[0:1], s[0:1], s[36:37]
	v_cmp_gt_i32_e64 s[30:31], 51, v94
	v_cndmask_b32_e64 v93, v93, v143, s[0:1]
	s_and_b64 s[0:1], s[0:1], s[34:35]
	v_cmp_gt_i32_e64 s[28:29], 50, v94
	v_cndmask_b32_e64 v92, v92, v143, s[0:1]
	s_and_b64 s[0:1], s[0:1], s[30:31]
	v_cmp_gt_i32_e64 s[26:27], 49, v94
	v_cndmask_b32_e64 v91, v91, v143, s[0:1]
	s_and_b64 s[0:1], s[0:1], s[28:29]
	v_cmp_gt_i32_e64 s[24:25], 48, v94
	v_cndmask_b32_e64 v90, v90, v143, s[0:1]
	s_and_b64 s[0:1], s[0:1], s[26:27]
	v_cmp_gt_i32_e64 s[22:23], 43, v94
	v_cndmask_b32_e64 v89, v89, v143, s[0:1]
	s_and_b64 s[0:1], s[0:1], s[24:25]
	v_cmp_gt_i32_e64 s[20:21], 42, v94
	v_cndmask_b32_e64 v88, v88, v143, s[0:1]
	s_and_b64 s[0:1], s[0:1], s[22:23]
	v_cmp_gt_i32_e64 s[18:19], 41, v94
	v_cndmask_b32_e64 v87, v87, v143, s[0:1]
	s_and_b64 s[0:1], s[0:1], s[20:21]
	v_cmp_gt_i32_e64 s[16:17], 40, v94
	v_cndmask_b32_e64 v86, v86, v143, s[0:1]
	s_and_b64 s[0:1], s[0:1], s[18:19]
	v_cmp_gt_i32_e64 s[14:15], 35, v94
	v_cndmask_b32_e64 v85, v85, v143, s[0:1]
	s_and_b64 s[0:1], s[0:1], s[16:17]
	v_cmp_gt_i32_e64 s[12:13], 34, v94
	v_cndmask_b32_e64 v84, v84, v143, s[0:1]
	s_and_b64 s[0:1], s[0:1], s[14:15]
	v_cmp_gt_i32_e64 s[10:11], 33, v94
	v_cndmask_b32_e64 v83, v83, v143, s[0:1]
	s_and_b64 s[0:1], s[0:1], s[12:13]
	v_cmp_gt_i32_e32 vcc, 32, v94
	v_cndmask_b32_e64 v82, v82, v143, s[0:1]
	s_and_b64 s[0:1], s[0:1], s[10:11]
	s_and_b64 vcc, s[0:1], vcc
	v_cndmask_b32_e64 v121, v121, v143, s[70:71]
	v_cndmask_b32_e64 v120, v120, v143, s[68:69]
	v_cndmask_b32_e64 v123, v123, v143, s[66:67]
	v_cndmask_b32_e64 v122, v122, v143, s[64:65]
	v_cndmask_b32_e64 v125, v125, v143, s[62:63]
	v_cndmask_b32_e64 v124, v124, v143, s[60:61]
	v_cndmask_b32_e64 v127, v127, v143, s[58:59]
	v_cndmask_b32_e64 v126, v126, v143, s[56:57]
	v_cndmask_b32_e64 v131, v131, v143, s[54:55]
	v_cndmask_b32_e64 v130, v130, v143, s[52:53]
	v_cndmask_b32_e64 v133, v133, v143, s[50:51]
	v_cndmask_b32_e64 v132, v132, v143, s[48:49]
	v_cndmask_b32_e64 v135, v135, v143, s[46:47]
	v_cndmask_b32_e64 v134, v134, v143, s[44:45]
	v_cndmask_b32_e64 v137, v137, v143, s[42:43]
	v_cndmask_b32_e64 v139, v139, v143, s[0:1]
	v_cndmask_b32_e32 v138, v138, v143, vcc

; __global__ void __launch_bounds__(NTHREADS, 2) hybrid_fwd(Params P) {
	.amdhsa_kernel _Z10hybrid_fwd6Params
		.amdhsa_group_segment_fixed_size 0
		.amdhsa_private_segment_fixed_size 0
		.amdhsa_kernarg_size 408
		.amdhsa_user_sgpr_count 2
		.amdhsa_user_sgpr_dispatch_ptr 0
		.amdhsa_user_sgpr_queue_ptr 0
		.amdhsa_user_sgpr_kernarg_segment_ptr 1
		.amdhsa_user_sgpr_dispatch_id 0
		.amdhsa_user_sgpr_kernarg_preload_length 0
		.amdhsa_user_sgpr_kernarg_preload_offset 0
		.amdhsa_user_sgpr_private_segment_size 0
		.amdhsa_uses_dynamic_stack 0
		.amdhsa_enable_private_segment 0
		.amdhsa_system_sgpr_workgroup_id_x 1
		.amdhsa_system_sgpr_workgroup_id_y 0
		.amdhsa_system_sgpr_workgroup_id_z 0
		.amdhsa_system_sgpr_workgroup_info 0
		.amdhsa_system_vgpr_workitem_id 2
		.amdhsa_next_free_vgpr 256
		.amdhsa_next_free_sgpr 98
		.amdhsa_accum_offset 256
		.amdhsa_reserve_vcc 1
		.amdhsa_float_round_mode_32 0
		.amdhsa_float_round_mode_16_64 0
		.amdhsa_float_denorm_mode_32 3
		.amdhsa_float_denorm_mode_16_64 3
		.amdhsa_dx10_clamp 1
		.amdhsa_ieee_mode 1
		.amdhsa_fp16_overflow 0
		.amdhsa_tg_split 0
		.amdhsa_exception_fp_ieee_invalid_op 0
		.amdhsa_exception_fp_denorm_src 0
		.amdhsa_exception_fp_ieee_div_zero 0
		.amdhsa_exception_fp_ieee_overflow 0
		.amdhsa_exception_fp_ieee_underflow 0
		.amdhsa_exception_fp_ieee_inexact 0
		.amdhsa_exception_int_div_zero 0
	.end_amdhsa_kernel

; __global__ void __launch_bounds__(NTHREADS, 2) hybrid_fwd(Params P) {
amdhsa.kernels:
  - .agpr_count:     0
    .args:
      - .offset:         0
        .size:           152
        .value_kind:     by_value
      - .offset:         152
        .size:           4
        .value_kind:     hidden_block_count_x
      - .offset:         156
        .size:           4
        .value_kind:     hidden_block_count_y
      - .offset:         160
        .size:           4
        .value_kind:     hidden_block_count_z
      - .offset:         164
        .size:           2
        .value_kind:     hidden_group_size_x
      - .offset:         166
        .size:           2
        .value_kind:     hidden_group_size_y
      - .offset:         168
        .size:           2
        .value_kind:     hidden_group_size_z
      - .offset:         170
        .size:           2
        .value_kind:     hidden_remainder_x
      - .offset:         172
        .size:           2
        .value_kind:     hidden_remainder_y
      - .offset:         174
        .size:           2
        .value_kind:     hidden_remainder_z
      - .offset:         192
        .size:           8
        .value_kind:     hidden_global_offset_x
      - .offset:         200
        .size:           8
        .value_kind:     hidden_global_offset_y
      - .offset:         208
        .size:           8
        .value_kind:     hidden_global_offset_z
      - .offset:         216
        .size:           2
        .value_kind:     hidden_grid_dims
      - .offset:         240
        .size:           8
        .value_kind:     hidden_multigrid_sync_arg
      - .offset:         272
        .size:           4
        .value_kind:     hidden_dynamic_lds_size
    .group_segment_fixed_size: 0
    .kernarg_segment_align: 8
    .kernarg_segment_size: 408
    .language:       OpenCL C
    .language_version:
      - 2
      - 0
    .max_flat_workgroup_size: 512
    .name:           _Z10hybrid_fwd6Params
    .private_segment_fixed_size: 0
    .sgpr_count:     104
    .sgpr_spill_count: 108
    .symbol:         _Z10hybrid_fwd6Params.kd
    .uniform_work_group_size: 1
    .uses_dynamic_stack: false
    .vgpr_count:     256
    .vgpr_spill_count: 0
    .wavefront_size: 64
